# conversion schedule P=20864 G=7800, class-B share 1536
# baseline (speedup 1.0000x reference)
; #define LAS __attribute__((address_space(3)))
; template <class KA> __device__ __forceinline__ ConvTile conv_desc(KA a, int gidx, int lane) {
;     const int l = gidx / CT_LAYER; int r = gidx - l * CT_LAYER; unsigned char* lw = a->ws + WS_W + (size_t)l * LW_STRIDE;
;     const float* s0; const float* s1 = nullptr; const float* gs = nullptr; bf16* dst; int K, Nsrc, mode = 0, ntn;
;     if (r < CT_GU) { gs = a->in[1] + (size_t)l * DM; s0 = a->in[2] + (size_t)l * DM * DFF; s1 = a->in[3] + (size_t)l * DM * DFF; dst = (bf16*)(lw + LW_GU1); K = DM; Nsrc = DFF; mode = 1; ntn = NGU / 64; }
; template <class KA> __device__ __forceinline__ void convert_range(KA a, LAS unsigned char* lds, int t_lo, int t_hi, int rank, int nrank) {
;     int tid_ = threadIdx.x; asm volatile("" : "+v"(tid_));
;     const int lane = tid_ & 63, wave = __builtin_amdgcn_readfirstlane(tid_ >> 6); LAS unsigned short* tl = (LAS unsigned short*)(lds + wave * 16384);
;     const int stride = nrank * 8; int it = t_lo + rank * 8 + wave;
;     if (it >= t_hi) return;
;     f32x4w va[16], vb[16]; float ga[16], gb[16];
;     ConvTile ta = conv_desc(a, it, lane), tb = ta; conv_load(ta, va, ga);
.LBB0_11:
	s_or_b64 exec, exec, s[0:1]
	v_writelane_b32 v250, s8, 4
	s_cmp_eq_u32 s8, 0
	s_nop 0
	v_writelane_b32 v250, s9, 5
	v_writelane_b32 v250, s10, 6
	v_writelane_b32 v250, s11, 7
	s_cbranch_scc1 .LBB0_279
	s_mov_b32 s0, s67
	s_load_dword s40, s[70:71], 0x3f0
	v_mov_b32_e32 v1, v0
	s_add_u32 s2, s70, 0x3f0
	s_addc_u32 s3, s71, 0
	s_lshl_b32 s0, s0, 3
	s_waitcnt lgkmcnt(0)
	s_mov_b32 s28, s40
	s_nop 0
	v_readfirstlane_b32 s24, v1
	s_ashr_i32 s29, s24, 6
	s_add_i32 s41, s29, s0
	s_cmpk_gt_i32 s41, 0x517f
	s_cbranch_scc1 .LBB0_221
	s_mul_hi_i32 s0, s41, 0x9baade8f
	s_add_i32 s4, s0, s41
	s_load_dwordx2 s[0:1], s[70:71], 0xd8
	s_lshr_b32 s5, s4, 31
	s_ashr_i32 s4, s4, 14
	s_add_i32 s16, s4, s5
	s_mul_i32 s26, s16, 0xffff96c0
	s_add_i32 s26, s26, s41
	s_waitcnt lgkmcnt(0)
	s_add_u32 s42, s0, 0x200000
	s_addc_u32 s43, s1, 0
	s_ashr_i32 s17, s16, 31
	s_mul_i32 s1, s16, 0xd300000
	s_mul_hi_i32 s0, s16, 0xd300000
	s_add_u32 s12, s42, s1
	s_addc_u32 s13, s43, s0
	s_cmpk_gt_i32 s26, 0x157f
	s_cbranch_scc0 .LBB0_21
	s_cmpk_gt_u32 s26, 0x203f
	s_cbranch_scc0 .LBB0_22
	s_cmpk_gt_u32 s26, 0x3ebf
	s_cbranch_scc0 .LBB0_23
	s_cmpk_gt_u32 s26, 0x3eff
	s_cbranch_scc0 .LBB0_24
	s_cmpk_gt_u32 s26, 0x44ff
	s_cbranch_scc0 .LBB0_25
	s_cmpk_gt_u32 s26, 0x48ff
	s_cbranch_scc0 .LBB0_26
	s_cmpk_gt_u32 s26, 0x5e7f
	s_cbranch_scc0 .LBB0_27
	s_load_dwordx2 s[0:1], s[70:71], 0xc0
	s_add_i32 s27, s26, 0xffffa180
	s_mul_i32 s5, s16, 0x2b00000
	s_mul_hi_i32 s4, s16, 0x2b00000
	s_mov_b64 s[6:7], 0
	s_waitcnt lgkmcnt(0)
	s_add_u32 s0, s0, s5
	s_addc_u32 s1, s1, s4
	s_add_u32 s4, s12, 0xbc80000
	s_addc_u32 s5, s13, 0
	s_branch .LBB0_28

; template <class KA> __device__ __forceinline__ ConvTile conv_desc(KA a, int gidx, int lane) {
;     const int l = gidx / CT_LAYER; int r = gidx - l * CT_LAYER; unsigned char* lw = a->ws + WS_W + (size_t)l * LW_STRIDE;
;     const float* s0; const float* s1 = nullptr; const float* gs = nullptr; bf16* dst; int K, Nsrc, mode = 0, ntn;
;     if (r < CT_GU) { gs = a->in[1] + (size_t)l * DM; s0 = a->in[2] + (size_t)l * DM * DFF; s1 = a->in[3] + (size_t)l * DM * DFF; dst = (bf16*)(lw + LW_GU1); K = DM; Nsrc = DFF; mode = 1; ntn = NGU / 64; }
;     else if ((r -= CT_GU) < CT_D) { s0 = a->in[4] + (size_t)l * DFF * DM; dst = (bf16*)(lw + LW_D1); K = DFF; Nsrc = DM; ntn = DM / 64; }
;     else if ((r -= CT_D) < CT_IN) { gs = a->in[5] + (size_t)l * DM; s0 = a->in[6] + (size_t)l * DM * 15368; dst = (bf16*)(lw + LW_IN); K = DM; Nsrc = 15368; mode = 2; ntn = NZP / 64; }
; template <class KA> __device__ __forceinline__ void convert_range(KA a, LAS unsigned char* lds, int t_lo, int t_hi, int rank, int nrank) {
;     ...
;         const bool nb = (it + stride) < t_hi; tb = conv_desc(a, nb ? it + stride : it, lane); conv_load(tb, vb, gb);
;         conv_finish(ta, va, ga, tl, lane);
;         if (!nb) break;
;         it += stride;
;         const bool na = (it + stride) < t_hi; ta = conv_desc(a, na ? it + stride : it, lane); conv_load(ta, va, ga);
.LBB0_89:
	s_add_i32 s39, s41, s45
	s_cmpk_lt_i32 s39, 0x5180
	s_cselect_b64 s[10:11], -1, 0
	s_and_b64 s[4:5], s[10:11], exec
	s_cselect_b32 s56, s39, s41
	s_mul_hi_i32 s0, s56, 0x9baade8f
	s_add_i32 s0, s0, s56
	s_lshr_b32 s4, s0, 31
	s_ashr_i32 s0, s0, 14
	s_add_i32 s24, s0, s4
	s_mul_i32 s36, s24, 0xffff96c0
	s_add_i32 s36, s36, s56
	s_ashr_i32 s25, s24, 31
	s_mul_i32 s4, s24, 0xd300000
	s_mul_hi_i32 s0, s24, 0xd300000
	s_add_u32 s22, s42, s4
	s_addc_u32 s23, s43, s0
	s_cmpk_gt_i32 s36, 0x157f
	s_mov_b64 s[34:35], -1
	s_cbranch_scc0 .LBB0_112
	s_cmpk_gt_u32 s36, 0x203f
	s_cbranch_scc0 .LBB0_109
	s_cmpk_gt_u32 s36, 0x3ebf
	s_mov_b64 s[30:31], -1
	s_cbranch_scc0 .LBB0_107
	s_cmpk_gt_u32 s36, 0x3eff
	s_mov_b64 s[28:29], -1
	s_cbranch_scc0 .LBB0_105
	s_cmpk_gt_u32 s36, 0x44ff
	s_cbranch_scc0 .LBB0_102
	s_cmpk_gt_u32 s36, 0x48ff
	s_cbranch_scc0 .LBB0_99
	s_cmpk_gt_u32 s36, 0x5e7f
	s_mov_b64 s[4:5], -1
	s_cbranch_scc0 .LBB0_97
	s_load_dwordx2 s[4:5], s[70:71], 0xc0
	s_add_i32 s37, s36, 0xffffa180
	s_mul_i32 s6, s24, 0x2b00000
	s_mul_hi_i32 s0, s24, 0x2b00000
	s_waitcnt lgkmcnt(0)
	s_add_u32 s12, s4, s6
	s_addc_u32 s13, s5, s0
	s_add_u32 s6, s22, 0xbc80000
	s_addc_u32 s7, s23, 0
	s_mov_b64 s[4:5], 0

; #define LAS __attribute__((address_space(3)))
; __device__ __forceinline__ unsigned pk_bf16(float lo, float hi) { unsigned r; asm volatile("v_cvt_pk_bf16_f32 %0, %1, %2" : "=v"(r) : "v"(lo), "v"(hi)); return r; }
; template <class KA> __device__ __forceinline__ ConvTile conv_desc(KA a, int gidx, int lane) {
;     ...
;     int nti, kti; if (mode == 1 || mode == 2) { const int grp = r >> 7, w = r & 127; kti = w >> 2; nti = grp * 4 + (w & 3); } else { nti = r % ntn; kti = r / ntn; }
;     const int n0 = nti * 64, k0 = kti * 64, n = n0 + (lane & 15) * 4; const float* src = s0; int col = n; float sc = 1.f;
;     if (mode == 1) { const int b = (n >> 7) & 1; col = ((n >> 8) << 7) | (n & 127); src = b ? s1 : s0; }
;     else if (mode == 2) { int nl = n; if (n < NZ) { const int p_ = n & 255; nl = (n & ~255) + 64 * ((p_ >> 5) & 3) + 32 * (p_ >> 7) + (p_ & 31); }
;         col = win_src_col(nl); if (nl >= Z_AK && nl < Z_AO) sc = 0.0625f; }
;     else if (mode == 3) { src = (n & 128) ? s1 : s0; col = n & 127; }
;     if (col < 0) { sc = 0.f; col = 0; }
;     ConvTile t; t.sp = src + (size_t)(k0 + (lane >> 4)) * Nsrc + col; t.gs = (gs ? gs : a->in[1]) + k0 % DM + (lane >> 4); t.gm = gs ? 1.f : 0.f; t.dp = dst + (size_t)n0 * K + k0; t.K = K; t.Nsrc = Nsrc; t.sc = sc; return t;
; }
; __device__ __forceinline__ void conv_load(const ConvTile& t, f32x4w (&v)[16], float (&g)[16]) {
; #pragma unroll
;     for (int i = 0; i < 16; ++i) g[i] = t.gs[4 * i];
; #pragma unroll
;     for (int i = 0; i < 16; ++i) v[i] = __builtin_nontemporal_load((const f32x4w*)(t.sp + (size_t)(4 * i) * t.Nsrc));
; }
; __device__ __forceinline__ void conv_finish(const ConvTile& t, const f32x4w (&v)[16], const float (&gg)[16], LAS unsigned short* tl, int lane) {
;     const int nl = (lane & 15) * 4;
; #pragma unroll
;     for (int i = 0; i < 16; ++i) { const float g = (gg[i] * t.gm + (1.f - t.gm)) * t.sc;
;         LAS unsigned* w = (LAS unsigned*)(tl + (4 * i + (lane >> 4)) * 66 + nl); w[0] = pk_bf16(v[i][0] * g, v[i][1] * g); w[1] = pk_bf16(v[i][2] * g, v[i][3] * g); }
.LBB0_151:
	s_lshl_b32 s12, s58, 6
	v_or_b32_e32 v66, s12, v132
	s_ashr_i32 s13, s12, 31
	s_mul_i32 s0, s18, s13
	v_mul_lo_u32 v68, s19, v66
	v_mad_u64_u32 v[66:67], s[20:21], s18, v66, 0
	v_add3_u32 v67, v67, s0, v68
	s_bfe_i32 s0, s58, 0x10019
	s_lshr_b32 s0, s0, 21
	s_add_i32 s0, s12, s0
	s_and_b32 s0, s0, 0xfffff800
	s_sub_i32 s20, s12, s0
	s_ashr_i32 s21, s20, 31
	v_max_i32_e32 v130, 0, v164
	v_lshl_add_u64 v[66:67], v[66:67], 2, s[22:23]
	s_lshl_b64 s[20:21], s[20:21], 2
	v_lshl_add_u64 v[66:67], v[130:131], 2, v[66:67]
	s_waitcnt lgkmcnt(0)
	s_add_u32 s16, s16, s20
	v_sub_f32_e64 v130, 1.0, s38
	s_addc_u32 s17, s17, s21
	s_lshl_b64 s[18:19], s[18:19], 4
	s_waitcnt vmcnt(31)
	v_fma_f32 v68, s38, v143, v130
	v_lshlrev_b32_e32 v182, 2, v132
	v_mul_f32_e32 v137, v163, v68
	v_lshl_add_u64 v[68:69], v[66:67], 0, s[18:19]
	global_load_dword v180, v182, s[16:17]
	global_load_dword v179, v182, s[16:17] offset:16
	global_load_dword v178, v182, s[16:17] offset:32
	global_load_dword v177, v182, s[16:17] offset:48
	global_load_dword v175, v182, s[16:17] offset:64
	global_load_dword v173, v182, s[16:17] offset:80
	global_load_dword v171, v182, s[16:17] offset:96
	global_load_dword v169, v182, s[16:17] offset:112
	global_load_dword v176, v182, s[16:17] offset:128
	global_load_dword v174, v182, s[16:17] offset:144
	global_load_dword v172, v182, s[16:17] offset:160
	global_load_dword v170, v182, s[16:17] offset:176
	global_load_dword v168, v182, s[16:17] offset:192
	global_load_dword v167, v182, s[16:17] offset:208
	global_load_dword v166, v182, s[16:17] offset:224
	global_load_dword v165, v182, s[16:17] offset:240
	global_load_dwordx4 v[126:129], v[66:67], off nt
	v_lshl_add_u64 v[66:67], v[68:69], 0, s[18:19]
	v_lshl_add_u64 v[70:71], v[66:67], 0, s[18:19]
	global_load_dwordx4 v[122:125], v[68:69], off nt
	global_load_dwordx4 v[118:121], v[66:67], off nt
	v_lshl_add_u64 v[66:67], v[70:71], 0, s[18:19]
	v_lshl_add_u64 v[68:69], v[66:67], 0, s[18:19]
	global_load_dwordx4 v[114:117], v[70:71], off nt
	global_load_dwordx4 v[110:113], v[66:67], off nt
	v_lshl_add_u64 v[66:67], v[68:69], 0, s[18:19]
	v_lshl_add_u64 v[70:71], v[66:67], 0, s[18:19]
	global_load_dwordx4 v[106:109], v[68:69], off nt
	global_load_dwordx4 v[102:105], v[66:67], off nt
	v_lshl_add_u64 v[66:67], v[70:71], 0, s[18:19]
	v_lshl_add_u64 v[68:69], v[66:67], 0, s[18:19]
	global_load_dwordx4 v[98:101], v[70:71], off nt
	global_load_dwordx4 v[94:97], v[66:67], off nt
	v_lshl_add_u64 v[66:67], v[68:69], 0, s[18:19]
	global_load_dwordx4 v[90:93], v[68:69], off nt
	v_lshl_add_u64 v[68:69], v[66:67], 0, s[18:19]
	global_load_dwordx4 v[86:89], v[66:67], off nt
	v_lshl_add_u64 v[66:67], v[68:69], 0, s[18:19]
	global_load_dwordx4 v[82:85], v[68:69], off nt
	v_lshl_add_u64 v[68:69], v[66:67], 0, s[18:19]
	global_load_dwordx4 v[78:81], v[66:67], off nt
	v_lshl_add_u64 v[66:67], v[68:69], 0, s[18:19]
	s_waitcnt vmcnt(44)
	v_mul_f32_e32 v183, v2, v137
	global_load_dwordx4 v[74:77], v[68:69], off nt
	v_lshl_add_u64 v[68:69], v[66:67], 0, s[18:19]
	v_mul_f32_e32 v184, v3, v137
	global_load_dwordx4 v[70:73], v[66:67], off nt
	s_nop 0
	global_load_dwordx4 v[66:69], v[68:69], off nt
	v_cvt_pk_bf16_f32 v183, v183, v184
	ds_write_b32 v139, v183
	v_mul_f32_e32 v183, v4, v137
	v_mul_f32_e32 v137, v5, v137
	v_cvt_pk_bf16_f32 v137, v183, v137
	ds_write_b32 v139, v137 offset:4
	v_fma_f32 v137, s38, v145, v130
	v_mul_f32_e32 v137, v163, v137
	s_waitcnt vmcnt(46)
	v_mul_f32_e32 v183, v6, v137
	v_mul_f32_e32 v184, v7, v137
	v_cvt_pk_bf16_f32 v183, v183, v184
	ds_write_b32 v139, v183 offset:528
	v_mul_f32_e32 v183, v8, v137
	v_mul_f32_e32 v137, v9, v137
	v_cvt_pk_bf16_f32 v137, v183, v137
	ds_write_b32 v139, v137 offset:532
	v_fma_f32 v137, s38, v147, v130
	v_mul_f32_e32 v137, v163, v137
	s_waitcnt vmcnt(45)
	v_mul_f32_e32 v183, v10, v137
	v_mul_f32_e32 v184, v11, v137
	v_cvt_pk_bf16_f32 v183, v183, v184
	ds_write_b32 v139, v183 offset:1056
	v_mul_f32_e32 v183, v12, v137
	v_mul_f32_e32 v137, v13, v137
	v_cvt_pk_bf16_f32 v137, v183, v137
	ds_write_b32 v139, v137 offset:1060
	v_fma_f32 v137, s38, v149, v130
	v_mul_f32_e32 v137, v163, v137
	s_waitcnt vmcnt(44)
	v_mul_f32_e32 v183, v14, v137
	v_mul_f32_e32 v184, v15, v137
	v_cvt_pk_bf16_f32 v183, v183, v184
	ds_write_b32 v139, v183 offset:1584
	v_mul_f32_e32 v183, v16, v137
	v_mul_f32_e32 v137, v17, v137
	v_cvt_pk_bf16_f32 v137, v183, v137
	ds_write_b32 v139, v137 offset:1588
	v_fma_f32 v137, s38, v151, v130
	v_mul_f32_e32 v137, v163, v137
	s_waitcnt vmcnt(43)
	v_mul_f32_e32 v183, v18, v137
	v_mul_f32_e32 v184, v19, v137
	v_cvt_pk_bf16_f32 v183, v183, v184
	ds_write_b32 v139, v183 offset:2112
	v_mul_f32_e32 v183, v20, v137
	v_mul_f32_e32 v137, v21, v137
	v_cvt_pk_bf16_f32 v137, v183, v137
	ds_write_b32 v139, v137 offset:2116
	v_fma_f32 v137, s38, v152, v130
	v_mul_f32_e32 v137, v163, v137
	s_waitcnt vmcnt(42)
	v_mul_f32_e32 v183, v22, v137
	v_mul_f32_e32 v184, v23, v137
	v_cvt_pk_bf16_f32 v183, v183, v184
	ds_write_b32 v139, v183 offset:2640
	v_mul_f32_e32 v183, v24, v137
	v_mul_f32_e32 v137, v25, v137
	v_cvt_pk_bf16_f32 v137, v183, v137
	ds_write_b32 v139, v137 offset:2644
	v_fma_f32 v137, s38, v153, v130
	v_mul_f32_e32 v137, v163, v137
	s_waitcnt vmcnt(41)
	v_mul_f32_e32 v183, v26, v137
	v_mul_f32_e32 v184, v27, v137
	v_cvt_pk_bf16_f32 v183, v183, v184
	ds_write_b32 v139, v183 offset:3168
	v_mul_f32_e32 v183, v28, v137
	v_mul_f32_e32 v137, v29, v137
	v_cvt_pk_bf16_f32 v137, v183, v137
	ds_write_b32 v139, v137 offset:3172
	v_fma_f32 v137, s38, v154, v130
	v_mul_f32_e32 v137, v163, v137
	s_waitcnt vmcnt(40)
; #define LAS __attribute__((address_space(3)))
; __device__ __forceinline__ unsigned pk_bf16(float lo, float hi) { unsigned r; asm volatile("v_cvt_pk_bf16_f32 %0, %1, %2" : "=v"(r) : "v"(lo), "v"(hi)); return r; }
; __device__ __forceinline__ void conv_finish(const ConvTile& t, const f32x4w (&v)[16], const float (&gg)[16], LAS unsigned short* tl, int lane) {
;     const int nl = (lane & 15) * 4;
; #pragma unroll
;     for (int i = 0; i < 16; ++i) { const float g = (gg[i] * t.gm + (1.f - t.gm)) * t.sc;
;         LAS unsigned* w = (LAS unsigned*)(tl + (4 * i + (lane >> 4)) * 66 + nl); w[0] = pk_bf16(v[i][0] * g, v[i][1] * g); w[1] = pk_bf16(v[i][2] * g, v[i][3] * g); }
;     asm volatile("s_waitcnt lgkmcnt(0)" ::: "memory");
;     const int kc = (lane & 7) * 8;
; #pragma unroll
;     for (int q = 0; q < 8; ++q) { const int r = 8 * q + (lane >> 3); unsigned w[4];
; #pragma unroll
;         for (int e = 0; e < 4; ++e) w[e] = (unsigned)tl[(kc + 2 * e) * 66 + r] | ((unsigned)tl[(kc + 2 * e + 1) * 66 + r] << 16);
	v_mul_f32_e32 v183, v30, v137
	v_mul_f32_e32 v184, v31, v137
	v_cvt_pk_bf16_f32 v183, v183, v184
	ds_write_b32 v139, v183 offset:3696
	v_mul_f32_e32 v183, v32, v137
	v_mul_f32_e32 v137, v33, v137
	v_cvt_pk_bf16_f32 v137, v183, v137
	ds_write_b32 v139, v137 offset:3700
	v_fma_f32 v137, s38, v155, v130
	v_mul_f32_e32 v137, v163, v137
	s_waitcnt vmcnt(39)
	v_mul_f32_e32 v183, v34, v137
	v_mul_f32_e32 v184, v35, v137
	v_cvt_pk_bf16_f32 v183, v183, v184
	ds_write_b32 v139, v183 offset:4224
	v_mul_f32_e32 v183, v36, v137
	v_mul_f32_e32 v137, v37, v137
	v_cvt_pk_bf16_f32 v137, v183, v137
	ds_write_b32 v139, v137 offset:4228
	v_fma_f32 v137, s38, v156, v130
	v_mul_f32_e32 v137, v163, v137
	s_waitcnt vmcnt(38)
	v_mul_f32_e32 v183, v38, v137
	v_mul_f32_e32 v184, v39, v137
	v_cvt_pk_bf16_f32 v183, v183, v184
	ds_write_b32 v139, v183 offset:4752
	v_mul_f32_e32 v183, v40, v137
	v_mul_f32_e32 v137, v41, v137
	v_cvt_pk_bf16_f32 v137, v183, v137
	ds_write_b32 v139, v137 offset:4756
	v_fma_f32 v137, s38, v157, v130
	v_mul_f32_e32 v137, v163, v137
	s_waitcnt vmcnt(37)
	v_mul_f32_e32 v183, v42, v137
	v_mul_f32_e32 v184, v43, v137
	v_cvt_pk_bf16_f32 v183, v183, v184
	ds_write_b32 v139, v183 offset:5280
	v_mul_f32_e32 v183, v44, v137
	v_mul_f32_e32 v137, v45, v137
	v_cvt_pk_bf16_f32 v137, v183, v137
	ds_write_b32 v139, v137 offset:5284
	v_fma_f32 v137, s38, v158, v130
	v_mul_f32_e32 v137, v163, v137
	s_waitcnt vmcnt(36)
	v_mul_f32_e32 v183, v46, v137
	v_mul_f32_e32 v184, v47, v137
	v_cvt_pk_bf16_f32 v183, v183, v184
	ds_write_b32 v139, v183 offset:5808
	v_mul_f32_e32 v183, v48, v137
	v_mul_f32_e32 v137, v49, v137
	v_cvt_pk_bf16_f32 v137, v183, v137
	ds_write_b32 v139, v137 offset:5812
	v_fma_f32 v137, s38, v159, v130
	v_mul_f32_e32 v137, v163, v137
	s_waitcnt vmcnt(35)
	v_mul_f32_e32 v183, v50, v137
	v_mul_f32_e32 v184, v51, v137
	v_cvt_pk_bf16_f32 v183, v183, v184
	ds_write_b32 v139, v183 offset:6336
	v_mul_f32_e32 v183, v52, v137
	v_mul_f32_e32 v137, v53, v137
	v_cvt_pk_bf16_f32 v137, v183, v137
	ds_write_b32 v139, v137 offset:6340
	v_fma_f32 v137, s38, v160, v130
	v_mul_f32_e32 v137, v163, v137
	s_waitcnt vmcnt(34)
	v_mul_f32_e32 v183, v54, v137
	v_mul_f32_e32 v184, v55, v137
	v_cvt_pk_bf16_f32 v183, v183, v184
	ds_write_b32 v139, v183 offset:6864
	v_mul_f32_e32 v183, v56, v137
	v_mul_f32_e32 v137, v57, v137
	v_cvt_pk_bf16_f32 v137, v183, v137
	ds_write_b32 v139, v137 offset:6868
	v_fma_f32 v137, s38, v161, v130
	v_mul_f32_e32 v137, v163, v137
	s_waitcnt vmcnt(33)
	v_mul_f32_e32 v183, v58, v137
	v_mul_f32_e32 v184, v59, v137
	v_cvt_pk_bf16_f32 v183, v183, v184
	ds_write_b32 v139, v183 offset:7392
	v_mul_f32_e32 v183, v60, v137
	v_mul_f32_e32 v137, v61, v137
	v_fmac_f32_e32 v130, s38, v162
	v_cvt_pk_bf16_f32 v137, v183, v137
	v_mul_f32_e32 v130, v163, v130
	ds_write_b32 v139, v137 offset:7396
	s_waitcnt vmcnt(32)
	v_mul_f32_e32 v137, v62, v130
	v_mul_f32_e32 v183, v63, v130
	v_cvt_pk_bf16_f32 v137, v137, v183
	ds_write_b32 v139, v137 offset:7920
	v_mul_f32_e32 v137, v64, v130
	v_mul_f32_e32 v130, v65, v130
	v_cvt_pk_bf16_f32 v130, v137, v130
	ds_write_b32 v139, v130 offset:7924
	s_waitcnt lgkmcnt(0)
	ds_read_u16 v130, v133
	ds_read_u16 v183, v133 offset:16
	ds_read_u16 v190, v133 offset:32
	ds_read_u16 v191, v133 offset:48
	ds_read_u16 v192, v133 offset:64
	ds_read_u16 v193, v133 offset:80
	ds_read_u16 v194, v133 offset:96
	ds_read_u16 v195, v133 offset:112
	ds_read_u16 v137, v133 offset:132
	ds_read_u16 v196, v133 offset:148
	ds_read_u16 v197, v133 offset:164
	ds_read_u16 v198, v133 offset:180
	ds_read_u16 v199, v133 offset:196
	ds_read_u16 v200, v133 offset:212
	ds_read_u16 v201, v133 offset:228
	ds_read_u16 v202, v133 offset:244
	ds_read_u16 v185, v133 offset:264
	ds_read_u16 v203, v133 offset:280
	ds_read_u16 v204, v133 offset:296
	ds_read_u16 v205, v133 offset:312
	ds_read_u16 v206, v133 offset:328
	ds_read_u16 v207, v133 offset:344
	ds_read_u16 v208, v133 offset:360
	ds_read_u16 v209, v133 offset:376
	ds_read_u16 v186, v133 offset:396
	ds_read_u16 v210, v133 offset:412
	ds_read_u16 v211, v133 offset:428
	ds_read_u16 v212, v133 offset:444
	ds_read_u16 v213, v133 offset:460
	ds_read_u16 v214, v133 offset:476
	ds_read_u16 v215, v133 offset:492
	ds_read_u16 v216, v133 offset:508
	s_waitcnt lgkmcnt(14)
	v_lshl_or_b32 v184, v137, 16, v130
	ds_read_u16 v130, v133 offset:528
	ds_read_u16 v217, v133 offset:544
	ds_read_u16 v218, v133 offset:560
	ds_read_u16 v219, v133 offset:576
	ds_read_u16 v220, v133 offset:592
	ds_read_u16 v221, v133 offset:608
	ds_read_u16 v222, v133 offset:624
	ds_read_u16 v223, v133 offset:640
	ds_read_u16 v137, v133 offset:660
	ds_read_u16 v224, v133 offset:676
	ds_read_u16 v225, v133 offset:692
	ds_read_u16 v226, v133 offset:708
	ds_read_u16 v227, v133 offset:724
	ds_read_u16 v228, v133 offset:740
	ds_read_u16 v229, v133 offset:756
	ds_read_u16 v230, v133 offset:772
	s_waitcnt lgkmcnt(14)
; __device__ __forceinline__ void conv_finish(const ConvTile& t, const f32x4w (&v)[16], const float (&gg)[16], LAS unsigned short* tl, int lane) {
;     ...
;     for (int q = 0; q < 8; ++q) { const int r = 8 * q + (lane >> 3); unsigned w[4];
; #pragma unroll
;         for (int e = 0; e < 4; ++e) w[e] = (unsigned)tl[(kc + 2 * e) * 66 + r] | ((unsigned)tl[(kc + 2 * e + 1) * 66 + r] << 16);
;         __builtin_nontemporal_store((u32x4w){w[0], w[1], w[2], w[3]}, (u32x4w*)(t.dp + (size_t)r * t.K + kc)); }
; template <class KA> __device__ __forceinline__ void convert_range(KA a, LAS unsigned char* lds, int t_lo, int t_hi, int rank, int nrank) {
;     ...
;         if (!nb) break;
;         it += stride;
;         const bool na = (it + stride) < t_hi; ta = conv_desc(a, na ? it + stride : it, lane); conv_load(ta, va, ga);
;         conv_finish(tb, vb, gb, tl, lane);
	v_lshl_or_b32 v185, v186, 16, v185
	s_waitcnt lgkmcnt(7)
	v_lshl_or_b32 v186, v137, 16, v130
	ds_read_u16 v130, v133 offset:792
	ds_read_u16 v231, v133 offset:808
	ds_read_u16 v232, v133 offset:824
	ds_read_u16 v233, v133 offset:840
	ds_read_u16 v234, v133 offset:856
	ds_read_u16 v235, v133 offset:872
	ds_read_u16 v236, v133 offset:888
	ds_read_u16 v237, v133 offset:904
	ds_read_u16 v137, v133 offset:924
	ds_read_u16 v238, v133 offset:940
	ds_read_u16 v239, v133 offset:956
	ds_read_u16 v240, v133 offset:972
	ds_read_u16 v241, v133 offset:988
	ds_read_u16 v242, v133 offset:1004
	ds_read_u16 v243, v133 offset:1020
	ds_read_u16 v244, v133 offset:1036
	v_mad_u64_u32 v[188:189], s[16:17], s44, v134, 0
	s_waitcnt lgkmcnt(7)
	v_lshl_or_b32 v187, v137, 16, v130
	v_lshl_add_u64 v[188:189], v[188:189], 1, s[8:9]
	v_mov_b32_e32 v137, v131
	v_lshl_add_u64 v[188:189], v[188:189], 0, v[136:137]
	global_store_dwordx4 v[188:189], v[184:187], off nt
	v_mad_u64_u32 v[188:189], s[16:17], s44, v138, 0
	v_lshl_add_u64 v[188:189], v[188:189], 1, s[8:9]
	v_lshl_or_b32 v184, v196, 16, v183
	v_lshl_or_b32 v185, v210, 16, v203
	v_lshl_or_b32 v186, v224, 16, v217
	s_waitcnt lgkmcnt(6)
	v_lshl_or_b32 v187, v238, 16, v231
	v_lshl_add_u64 v[188:189], v[188:189], 0, v[136:137]
	global_store_dwordx4 v[188:189], v[184:187], off nt
	v_mad_u64_u32 v[188:189], s[16:17], s44, v140, 0
	v_lshl_add_u64 v[188:189], v[188:189], 1, s[8:9]
	v_lshl_or_b32 v184, v197, 16, v190
	v_lshl_or_b32 v185, v211, 16, v204
	v_lshl_or_b32 v186, v225, 16, v218
	s_waitcnt lgkmcnt(5)
	v_lshl_or_b32 v187, v239, 16, v232
	v_lshl_add_u64 v[188:189], v[188:189], 0, v[136:137]
	global_store_dwordx4 v[188:189], v[184:187], off nt
	v_mad_u64_u32 v[188:189], s[16:17], s44, v142, 0
	v_lshl_add_u64 v[188:189], v[188:189], 1, s[8:9]
	v_lshl_or_b32 v184, v198, 16, v191
	v_lshl_or_b32 v185, v212, 16, v205
	v_lshl_or_b32 v186, v226, 16, v219
	s_waitcnt lgkmcnt(4)
	v_lshl_or_b32 v187, v240, 16, v233
	v_lshl_add_u64 v[188:189], v[188:189], 0, v[136:137]
	global_store_dwordx4 v[188:189], v[184:187], off nt
	v_mad_u64_u32 v[188:189], s[16:17], s44, v144, 0
	v_lshl_add_u64 v[188:189], v[188:189], 1, s[8:9]
	v_lshl_or_b32 v184, v199, 16, v192
	v_lshl_or_b32 v185, v213, 16, v206
	v_lshl_or_b32 v186, v227, 16, v220
	s_waitcnt lgkmcnt(3)
	v_lshl_or_b32 v187, v241, 16, v234
	v_lshl_add_u64 v[188:189], v[188:189], 0, v[136:137]
	global_store_dwordx4 v[188:189], v[184:187], off nt
	v_mad_u64_u32 v[188:189], s[16:17], s44, v146, 0
	v_lshl_add_u64 v[188:189], v[188:189], 1, s[8:9]
	v_lshl_or_b32 v184, v200, 16, v193
	v_lshl_or_b32 v185, v214, 16, v207
	v_lshl_or_b32 v186, v228, 16, v221
	s_waitcnt lgkmcnt(2)
	v_lshl_or_b32 v187, v242, 16, v235
	v_lshl_add_u64 v[188:189], v[188:189], 0, v[136:137]
	global_store_dwordx4 v[188:189], v[184:187], off nt
	v_mad_u64_u32 v[188:189], s[16:17], s44, v148, 0
	v_lshl_add_u64 v[188:189], v[188:189], 1, s[8:9]
	v_lshl_or_b32 v184, v201, 16, v194
	v_lshl_or_b32 v185, v215, 16, v208
	v_lshl_or_b32 v186, v229, 16, v222
	s_waitcnt lgkmcnt(1)
	v_lshl_or_b32 v187, v243, 16, v236
	v_lshl_add_u64 v[188:189], v[188:189], 0, v[136:137]
	global_store_dwordx4 v[188:189], v[184:187], off nt
	v_mad_u64_u32 v[188:189], s[16:17], s44, v150, 0
	v_lshl_add_u64 v[188:189], v[188:189], 1, s[8:9]
	v_lshl_or_b32 v184, v202, 16, v195
	v_lshl_or_b32 v185, v216, 16, v209
	v_lshl_or_b32 v186, v230, 16, v223
	s_waitcnt lgkmcnt(0)
	v_lshl_or_b32 v187, v244, 16, v237
	v_lshl_add_u64 v[188:189], v[188:189], 0, v[136:137]
	global_store_dwordx4 v[188:189], v[184:187], off nt
	s_waitcnt lgkmcnt(0)
	s_andn2_b64 vcc, exec, s[10:11]
	s_mov_b64 s[10:11], 0
	s_cbranch_vccnz .LBB0_88
	s_add_i32 s0, s39, s45
	s_cmpk_lt_i32 s0, 0x5180
	s_cselect_b64 s[10:11], -1, 0
	s_and_b64 s[8:9], s[10:11], exec
	s_cselect_b32 s41, s0, s39
	s_mul_hi_i32 s0, s41, 0x9baade8f
	s_add_i32 s0, s0, s41
	s_lshr_b32 s8, s0, 31
	s_ashr_i32 s0, s0, 14
	s_add_i32 s26, s0, s8
	s_mul_i32 s38, s26, 0xffff96c0
	s_add_i32 s38, s38, s41
	s_ashr_i32 s27, s26, 31
	s_mul_i32 s8, s26, 0xd300000
	s_mul_hi_i32 s0, s26, 0xd300000
	s_add_u32 s24, s42, s8
	s_addc_u32 s25, s43, s0
	s_cmpk_gt_i32 s38, 0x157f
	s_mov_b64 s[36:37], -1
	s_cbranch_scc0 .LBB0_165
	s_cmpk_gt_u32 s38, 0x203f
	s_cbranch_scc0 .LBB0_218
	s_cmpk_gt_u32 s38, 0x3ebf
	s_mov_b64 s[34:35], -1
	s_cbranch_scc0 .LBB0_216
	s_cmpk_gt_u32 s38, 0x3eff
	s_mov_b64 s[30:31], -1
	s_cbranch_scc0 .LBB0_214
	s_cmpk_gt_u32 s38, 0x44ff
	s_cbranch_scc0 .LBB0_211
	s_cmpk_gt_u32 s38, 0x48ff
	s_cbranch_scc0 .LBB0_208
	s_cmpk_gt_u32 s38, 0x5e7f
	s_mov_b64 s[18:19], -1
	s_cbranch_scc0 .LBB0_160
	s_load_dwordx2 s[8:9], s[70:71], 0xc0
	s_add_i32 s39, s38, 0xffffa180
	s_mul_i32 s16, s26, 0x2b00000
	s_mul_hi_i32 s0, s26, 0x2b00000
	s_mov_b64 s[18:19], 0
	s_waitcnt lgkmcnt(0)
	s_add_u32 s16, s8, s16
	s_addc_u32 s17, s9, s0
	s_add_u32 s8, s24, 0xbc80000
	s_addc_u32 s9, s25, 0

; #define KP() ({ KArgs kp_ = kp0; asm volatile("" : "+s"(kp_)); kp_; })
; #define G_ ({ int g__ = (int)gridDim.x; asm volatile("" : "+s"(g__)); g__; })
; #define c_ ({ int c__ = (int)blockIdx.x; asm volatile("" : "+s"(c__)); c__; })
; __global__ void __launch_bounds__(512, 2) mega(MegaArgs a) {
;     ...
;             { const int rem = ((T_SEQ / 256) * (NGU / 256)) % G_, q = 3 * l + (half ? 2 : 0), hi = cvt_slot_hi(q) < CVT_TOTAL ? cvt_slot_hi(q) : CVT_TOTAL;
;               if (!(hf & 2) && rem && c_ >= rem && cvt_slot_lo(q) < hi) { KArgs kq = KP(); convert_range(kq, lds, cvt_slot_lo(q), hi, c_ - rem, G_ - rem); } }
.LBB0_308:
	s_mov_b32 s0, s21
	s_abs_i32 s0, s0
	v_cvt_f32_u32_e32 v1, s0
	s_sub_i32 s1, 0, s0
	v_rcp_iflag_f32_e32 v1, v1
	s_nop 0
	v_mul_f32_e32 v1, 0x4f7ffffe, v1
	v_cvt_u32_f32_e32 v1, v1
	s_nop 0
	v_readfirstlane_b32 s2, v1
	s_mul_i32 s1, s1, s2
	s_mul_hi_u32 s1, s2, s1
	s_add_i32 s2, s2, s1
	s_mul_hi_u32 s1, s2, 0x560
	s_mul_i32 s1, s1, s0
	s_sub_i32 s1, 0x560, s1
	s_sub_i32 s2, s1, s0
	s_cmp_ge_u32 s1, s0
	s_cselect_b32 s1, s2, s1
	s_sub_i32 s2, s1, s0
	s_cmp_ge_u32 s1, s0
	v_readlane_b32 s0, v251, 24
	s_cselect_b32 s44, s2, s1
	s_movk_i32 s44, 0xa0
	s_bitcmp1_b32 s0, 1
	s_cselect_b64 s[0:1], -1, 0
	s_cmp_eq_u32 s44, 0
	s_cselect_b64 s[4:5], -1, 0
	s_or_b64 s[0:1], s[0:1], s[4:5]
	s_and_b64 vcc, exec, s[0:1]
	s_cbranch_vccnz .LBB0_496
	v_readlane_b32 s0, v251, 22
	v_readlane_b32 s1, v251, 23
	s_mul_i32 s0, s0, 3
	s_lshl_b32 s1, s52, 1
	s_add_i32 s1, s1, s0
	s_mul_hi_i32 s0, s1, 0x55555556
	s_lshr_b32 s2, s0, 31
	s_add_i32 s0, s0, s2
	s_mul_i32 s2, s0, 3
	s_sub_i32 s1, s1, s2
	s_cmp_eq_u32 s1, 1
	s_movk_i32 s2, 0x1e78
	s_movk_i32 s4, 0x1ce8
	s_cselect_b32 s2, s2, 0x3b60
	s_cselect_b32 s4, s4, 0x1e78
	s_cmp_lg_u32 s1, 0
	s_mulk_i32 s0, 0x59d8
	s_cselect_b32 s1, s2, 0
	s_add_i32 s2, s0, s1
	s_addk_i32 s2, 0x5180
	s_add_i32 s0, s2, s4
	s_min_i32 s26, s0, 0x1a500
	s_mov_b32 s0, s67
	s_cmp_ge_i32 s0, s44
	s_cselect_b64 s[0:1], -1, 0
	s_cmp_lt_i32 s2, s26
	s_cselect_b64 s[4:5], -1, 0
	s_and_b64 s[0:1], s[0:1], s[4:5]
	s_andn2_b64 vcc, exec, s[0:1]
	s_cbranch_vccnz .LBB0_496
	s_mov_b64 s[0:1], s[70:71]
	s_mov_b32 s4, s67
	s_sub_i32 s4, s4, s44
	s_mov_b32 s45, s21
	s_cmp_lt_u32 s4, 32
	s_cbranch_scc1 .Lrb1_B
	s_sub_i32 s4, s4, 32
	s_movk_i32 s44, 0xc0
	s_addk_i32 s2, 0x600
	s_branch .Lrb1_done
.Lrb1_B:
	s_movk_i32 s45, 0xc0
	s_add_i32 s27, s2, 0x600
	s_min_i32 s26, s26, s27

; #define KP() ({ KArgs kp_ = kp0; asm volatile("" : "+s"(kp_)); kp_; })
; #define G_ ({ int g__ = (int)gridDim.x; asm volatile("" : "+s"(g__)); g__; })
; #define c_ ({ int c__ = (int)blockIdx.x; asm volatile("" : "+s"(c__)); c__; })
; __global__ void __launch_bounds__(512, 2) mega(MegaArgs a) {
;     ...
;                 { const int rem = ((T_SEQ / 256) * (NZP / 256)) % G_, q = 3 * l + 1, hi = cvt_slot_hi(q) < CVT_TOTAL ? cvt_slot_hi(q) : CVT_TOTAL;
;                   if (!(hf & 2) && rem && c_ >= rem && cvt_slot_lo(q) < hi) { KArgs kq = KP(); convert_range(kq, lds, cvt_slot_lo(q), hi, c_ - rem, G_ - rem); } }
.LBB0_693:
	s_mov_b32 s0, s21
	s_abs_i32 s0, s0
	v_cvt_f32_u32_e32 v1, s0
	s_sub_i32 s1, 0, s0
	v_rcp_iflag_f32_e32 v1, v1
	s_nop 0
	v_mul_f32_e32 v1, 0x4f7ffffe, v1
	v_cvt_u32_f32_e32 v1, v1
	s_nop 0
	v_readfirstlane_b32 s2, v1
	s_mul_i32 s1, s1, s2
	s_mul_hi_u32 s1, s2, s1
	s_add_i32 s2, s2, s1
	s_mul_hi_u32 s1, s2, 0x7a0
	s_mul_i32 s1, s1, s0
	s_sub_i32 s1, 0x7a0, s1
	s_sub_i32 s2, s1, s0
	s_cmp_ge_u32 s1, s0
	s_cselect_b32 s1, s2, s1
	s_sub_i32 s2, s1, s0
	s_cmp_ge_u32 s1, s0
	v_readlane_b32 s0, v251, 24
	s_cselect_b32 s44, s2, s1
	s_bitcmp1_b32 s0, 1
	s_cselect_b64 s[0:1], -1, 0
	s_cmp_eq_u32 s44, 0
	s_waitcnt lgkmcnt(0)
	s_cselect_b64 s[4:5], -1, 0
	s_or_b64 s[0:1], s[0:1], s[4:5]
	s_and_b64 vcc, exec, s[0:1]
	s_cbranch_vccnz .LBB0_881
	v_readlane_b32 s0, v251, 22
	s_mul_i32 s0, s0, 3
	v_readlane_b32 s1, v251, 23
	s_add_i32 s0, s0, 1
	s_mul_hi_i32 s1, s0, 0x55555556
	s_lshr_b32 s2, s1, 31
	s_add_i32 s1, s1, s2
	s_mul_i32 s2, s1, 3
	s_sub_i32 s0, s0, s2
	s_cmp_eq_u32 s0, 1
	s_movk_i32 s2, 0x1e78
	s_movk_i32 s4, 0x1ce8
	s_cselect_b32 s2, s2, 0x3b60
	s_cselect_b32 s4, s4, 0x1e78
	s_cmp_lg_u32 s0, 0
	s_mul_i32 s0, s1, 0x59d8
	s_cselect_b32 s1, s2, 0
	s_add_i32 s2, s0, s1
	s_addk_i32 s2, 0x5180
	s_add_i32 s0, s2, s4
	s_min_i32 s26, s0, 0x1a500
	s_mov_b32 s0, s67
	s_cmp_ge_i32 s0, s44
	s_cselect_b64 s[0:1], -1, 0
	s_cmp_lt_i32 s2, s26
	s_cselect_b64 s[4:5], -1, 0
	s_and_b64 s[0:1], s[0:1], s[4:5]
	s_andn2_b64 vcc, exec, s[0:1]
	s_cbranch_vccnz .LBB0_881
	s_mov_b64 s[0:1], s[70:71]
	s_mov_b32 s4, s67
	s_sub_i32 s4, s4, s44
	s_mov_b32 s45, s21
	v_mov_b32_e32 v1, v0
	s_lshl_b32 s4, s4, 3
	v_readfirstlane_b32 s47, v1
	s_ashr_i32 s46, s47, 6
	s_add_i32 s2, s4, s2
	s_add_i32 s27, s2, s46
	s_cmp_ge_i32 s27, s26
	s_cbranch_scc1 .LBB0_881
	s_mul_hi_i32 s2, s27, 0x9baade8f
	s_add_i32 s2, s2, s27
	s_load_dwordx2 s[4:5], s[0:1], 0xd8
	s_lshr_b32 s6, s2, 31
	s_ashr_i32 s2, s2, 14
	s_add_i32 s30, s2, s6
	s_mul_i32 s42, s30, 0xffff96c0
	s_add_i32 s42, s42, s27
	s_waitcnt lgkmcnt(0)
	s_add_u32 s52, s4, 0x200000
	s_addc_u32 s53, s5, 0
	s_ashr_i32 s31, s30, 31
	s_mul_i32 s4, s30, 0xd300000
	s_mul_hi_i32 s2, s30, 0xd300000
	s_add_u32 s28, s52, s4
	s_addc_u32 s29, s53, s2
	s_cmpk_gt_i32 s42, 0x157f
	s_mov_b64 s[40:41], -1
	s_cbranch_scc0 .LBB0_706
	s_cmpk_gt_u32 s42, 0x203f
	s_cbranch_scc1 .LBB0_698
	s_getpc_b64 s[98:99]
